# v012 plus the two remaining P7 main-loop MFMA blocks reordered into back-to-back accumulator pairs
# speedup vs baseline: 1.0029x; 1.0029x over previous
.LBB0_604:
	ds_read_b128 v[16:19], v176
	ds_read_b128 v[20:23], v176 offset:1024
	ds_read_b128 v[32:35], v176 offset:2048
	ds_read_b128 v[36:39], v176 offset:3072
	s_add_u32 s41, s10, 0xfff00080
	s_addc_u32 s46, s11, -1
	s_cmp_eq_u32 s39, 60
	s_cselect_b32 s49, s4, s46
	s_cselect_b32 s48, s5, s41
	s_cselect_b32 s47, s6, s15
	s_cselect_b32 s46, s7, s13
	v_lshl_add_u64 v[160:161], s[10:11], 0, v[152:153]
	s_add_i32 m0, s52, 0xc000
	ds_read_b128 v[164:167], v177
	ds_read_b128 v[168:171], v177 offset:1024
	ds_read_b128 v[190:193], v177 offset:2048
	ds_read_b128 v[194:197], v177 offset:3072
	ds_read_b128 v[198:201], v177 offset:4096
	ds_read_b128 v[202:205], v177 offset:5120
	ds_read_b128 v[206:209], v177 offset:6144
	ds_read_b128 v[210:213], v177 offset:7168
	global_load_lds_dwordx4 v[160:161], off
	v_lshl_add_u64 v[160:161], s[10:11], 0, v[154:155]
	s_add_i32 m0, s52, 0xe000
	s_nop 0
	global_load_lds_dwordx4 v[160:161], off
	s_waitcnt lgkmcnt(8)
	s_barrier
	s_waitcnt lgkmcnt(0)
	s_setprio 1
	s_waitcnt lgkmcnt(0)
	v_mfma_f32_16x16x32_bf16 v[140:143], v[16:19], v[164:167], v[140:143]
	v_mfma_f32_16x16x32_bf16 v[140:143], v[20:23], v[168:171], v[140:143]
	v_mfma_f32_16x16x32_bf16 v[136:139], v[32:35], v[164:167], v[136:139]
	v_mfma_f32_16x16x32_bf16 v[136:139], v[36:39], v[168:171], v[136:139]
	v_mfma_f32_16x16x32_bf16 v[124:127], v[16:19], v[190:193], v[124:127]
	v_mfma_f32_16x16x32_bf16 v[124:127], v[20:23], v[194:197], v[124:127]
	v_mfma_f32_16x16x32_bf16 v[120:123], v[32:35], v[190:193], v[120:123]
	v_mfma_f32_16x16x32_bf16 v[120:123], v[36:39], v[194:197], v[120:123]
	v_mfma_f32_16x16x32_bf16 v[108:111], v[16:19], v[198:201], v[108:111]
	v_mfma_f32_16x16x32_bf16 v[108:111], v[20:23], v[202:205], v[108:111]
	v_mfma_f32_16x16x32_bf16 v[104:107], v[32:35], v[198:201], v[104:107]
	v_mfma_f32_16x16x32_bf16 v[104:107], v[36:39], v[202:205], v[104:107]
	v_mfma_f32_16x16x32_bf16 v[92:95], v[16:19], v[206:209], v[92:95]
	v_mfma_f32_16x16x32_bf16 v[92:95], v[20:23], v[210:213], v[92:95]
	v_mfma_f32_16x16x32_bf16 v[88:91], v[32:35], v[206:209], v[88:91]
	v_mfma_f32_16x16x32_bf16 v[88:91], v[36:39], v[210:213], v[88:91]
	s_setprio 0
	s_barrier
	s_add_i32 s41, s81, s51
	v_lshl_add_u64 v[160:161], s[46:47], 0, v[146:147]
	s_mov_b32 m0, s41
	ds_read_b128 v[214:217], v178
	ds_read_b128 v[218:221], v178 offset:1024
	ds_read_b128 v[222:225], v178 offset:2048
	ds_read_b128 v[226:229], v178 offset:3072
	global_load_lds_dwordx4 v[160:161], off
	v_lshl_add_u64 v[230:231], s[46:47], 0, v[150:151]
	s_add_i32 m0, s41, 0x2000
	s_nop 0
	global_load_lds_dwordx4 v[230:231], off
	s_barrier
	s_waitcnt lgkmcnt(0)
	s_setprio 1
	s_waitcnt lgkmcnt(0)
	v_mfma_f32_16x16x32_bf16 v[132:135], v[214:217], v[164:167], v[132:135]
	v_mfma_f32_16x16x32_bf16 v[132:135], v[218:221], v[168:171], v[132:135]
	v_mfma_f32_16x16x32_bf16 v[128:131], v[222:225], v[164:167], v[128:131]
	v_mfma_f32_16x16x32_bf16 v[128:131], v[226:229], v[168:171], v[128:131]
	v_mfma_f32_16x16x32_bf16 v[116:119], v[214:217], v[190:193], v[116:119]
	v_mfma_f32_16x16x32_bf16 v[116:119], v[218:221], v[194:197], v[116:119]
	v_mfma_f32_16x16x32_bf16 v[112:115], v[222:225], v[190:193], v[112:115]
	v_mfma_f32_16x16x32_bf16 v[112:115], v[226:229], v[194:197], v[112:115]
	v_mfma_f32_16x16x32_bf16 v[100:103], v[214:217], v[198:201], v[100:103]
	v_mfma_f32_16x16x32_bf16 v[100:103], v[218:221], v[202:205], v[100:103]
	v_mfma_f32_16x16x32_bf16 v[96:99], v[222:225], v[198:201], v[96:99]
	v_mfma_f32_16x16x32_bf16 v[96:99], v[226:229], v[202:205], v[96:99]
	v_mfma_f32_16x16x32_bf16 v[84:87], v[214:217], v[206:209], v[84:87]
	v_mfma_f32_16x16x32_bf16 v[84:87], v[218:221], v[210:213], v[84:87]
	v_mfma_f32_16x16x32_bf16 v[80:83], v[222:225], v[206:209], v[80:83]
	v_mfma_f32_16x16x32_bf16 v[80:83], v[226:229], v[210:213], v[80:83]
	s_setprio 0
	s_mov_b32 m0, s52
	v_lshl_add_u64 v[232:233], s[48:49], 0, v[144:145]
	s_barrier
	ds_read_b128 v[164:167], v177 offset:16384
	ds_read_b128 v[168:171], v177 offset:17408
	ds_read_b128 v[190:193], v177 offset:18432
	ds_read_b128 v[194:197], v177 offset:19456
	ds_read_b128 v[198:201], v177 offset:20480
	ds_read_b128 v[202:205], v177 offset:21504
	ds_read_b128 v[206:209], v177 offset:22528
	ds_read_b128 v[210:213], v177 offset:23552
	global_load_lds_dwordx4 v[232:233], off
	v_lshl_add_u64 v[234:235], s[48:49], 0, v[148:149]
	s_mov_b32 m0, s53
	s_nop 0
	global_load_lds_dwordx4 v[234:235], off
	s_barrier
	s_waitcnt lgkmcnt(0)
	s_setprio 1
	s_waitcnt lgkmcnt(0)
	v_mfma_f32_16x16x32_bf16 v[76:79], v[16:19], v[164:167], v[76:79]
	v_mfma_f32_16x16x32_bf16 v[76:79], v[20:23], v[168:171], v[76:79]
	v_mfma_f32_16x16x32_bf16 v[72:75], v[32:35], v[164:167], v[72:75]
	v_mfma_f32_16x16x32_bf16 v[72:75], v[36:39], v[168:171], v[72:75]
	v_mfma_f32_16x16x32_bf16 v[60:63], v[16:19], v[190:193], v[60:63]
	v_mfma_f32_16x16x32_bf16 v[60:63], v[20:23], v[194:197], v[60:63]
	v_mfma_f32_16x16x32_bf16 v[56:59], v[32:35], v[190:193], v[56:59]
	v_mfma_f32_16x16x32_bf16 v[56:59], v[36:39], v[194:197], v[56:59]
	v_mfma_f32_16x16x32_bf16 v[44:47], v[16:19], v[198:201], v[44:47]
	v_mfma_f32_16x16x32_bf16 v[44:47], v[20:23], v[202:205], v[44:47]
	v_mfma_f32_16x16x32_bf16 v[40:43], v[32:35], v[198:201], v[40:43]
	v_mfma_f32_16x16x32_bf16 v[40:43], v[36:39], v[202:205], v[40:43]
	v_mfma_f32_16x16x32_bf16 v[12:15], v[16:19], v[206:209], v[12:15]
	v_mfma_f32_16x16x32_bf16 v[12:15], v[20:23], v[210:213], v[12:15]
	v_mfma_f32_16x16x32_bf16 v[8:11], v[32:35], v[206:209], v[8:11]
	v_mfma_f32_16x16x32_bf16 v[8:11], v[36:39], v[210:213], v[8:11]
	s_setprio 0
	s_barrier
	s_add_u32 s54, s46, 0x100000
	s_addc_u32 s55, s47, 0
	s_add_i32 s41, s82, s51
	v_lshl_add_u64 v[16:17], s[54:55], 0, v[146:147]
	s_mov_b32 m0, s41
	s_nop 0
	global_load_lds_dwordx4 v[16:17], off
	v_lshl_add_u64 v[16:17], s[54:55], 0, v[150:151]
	s_add_i32 m0, s41, 0x2000
	s_nop 0
	global_load_lds_dwordx4 v[16:17], off
	s_waitcnt vmcnt(6)
	s_barrier
	s_setprio 1
	v_mfma_f32_16x16x32_bf16 v[28:31], v[214:217], v[198:201], v[28:31]
	v_mfma_f32_16x16x32_bf16 v[28:31], v[218:221], v[202:205], v[28:31]
	v_mfma_f32_16x16x32_bf16 v[24:27], v[222:225], v[198:201], v[24:27]
	v_mfma_f32_16x16x32_bf16 v[24:27], v[226:229], v[202:205], v[24:27]
	v_mfma_f32_16x16x32_bf16 v[4:7], v[214:217], v[206:209], v[4:7]
	v_mfma_f32_16x16x32_bf16 v[4:7], v[218:221], v[210:213], v[4:7]
	v_mfma_f32_16x16x32_bf16 v[0:3], v[222:225], v[206:209], v[0:3]
	v_mfma_f32_16x16x32_bf16 v[0:3], v[226:229], v[210:213], v[0:3]
	v_mfma_f32_16x16x32_bf16 v[16:19], v[214:217], v[164:167], v[68:71]
	v_mfma_f32_16x16x32_bf16 v[16:19], v[218:221], v[168:171], v[16:19]
	v_mfma_f32_16x16x32_bf16 v[20:23], v[222:225], v[164:167], v[64:67]
	v_mfma_f32_16x16x32_bf16 v[20:23], v[226:229], v[168:171], v[20:23]
	v_mfma_f32_16x16x32_bf16 v[32:35], v[214:217], v[190:193], v[52:55]
	v_mfma_f32_16x16x32_bf16 v[32:35], v[218:221], v[194:197], v[32:35]
	v_mfma_f32_16x16x32_bf16 v[36:39], v[222:225], v[190:193], v[48:51]
	v_mfma_f32_16x16x32_bf16 v[36:39], v[226:229], v[194:197], v[36:39]
	s_setprio 0
	s_add_i32 s41, 0, 0x18000
	v_add_u32_e32 v68, s41, v174
	s_barrier
	ds_read_b128 v[48:51], v68
	ds_read_b128 v[52:55], v68 offset:1024
	ds_read_b128 v[64:67], v68 offset:2048
	ds_read_b128 v[68:71], v68 offset:3072
	s_add_u32 s48, s48, 0x100000
	s_addc_u32 s49, s49, 0
	s_mov_b32 m0, s61
	v_lshl_add_u64 v[214:215], s[48:49], 0, v[144:145]
	ds_read_b128 v[164:167], v177 offset:32768
	ds_read_b128 v[168:171], v177 offset:33792
	ds_read_b128 v[190:193], v177 offset:34816
	ds_read_b128 v[194:197], v177 offset:35840
	ds_read_b128 v[198:201], v177 offset:36864
	ds_read_b128 v[202:205], v177 offset:37888
	ds_read_b128 v[206:209], v177 offset:38912
	ds_read_b128 v[210:213], v177 offset:39936
	global_load_lds_dwordx4 v[214:215], off
	v_lshl_add_u64 v[214:215], s[48:49], 0, v[148:149]
	s_mov_b32 m0, s74
	s_nop 0
	global_load_lds_dwordx4 v[214:215], off
	s_waitcnt lgkmcnt(8)
	s_barrier
	s_waitcnt lgkmcnt(0)
	s_setprio 1
	s_waitcnt lgkmcnt(0)
	v_mfma_f32_16x16x32_bf16 v[140:143], v[48:51], v[164:167], v[140:143]
	v_mfma_f32_16x16x32_bf16 v[140:143], v[52:55], v[168:171], v[140:143]
	v_mfma_f32_16x16x32_bf16 v[136:139], v[64:67], v[164:167], v[136:139]
	v_mfma_f32_16x16x32_bf16 v[136:139], v[68:71], v[168:171], v[136:139]
	v_mfma_f32_16x16x32_bf16 v[124:127], v[48:51], v[190:193], v[124:127]
	v_mfma_f32_16x16x32_bf16 v[124:127], v[52:55], v[194:197], v[124:127]
	v_mfma_f32_16x16x32_bf16 v[120:123], v[64:67], v[190:193], v[120:123]
	v_mfma_f32_16x16x32_bf16 v[120:123], v[68:71], v[194:197], v[120:123]
	v_mfma_f32_16x16x32_bf16 v[108:111], v[48:51], v[198:201], v[108:111]
	v_mfma_f32_16x16x32_bf16 v[108:111], v[52:55], v[202:205], v[108:111]
	v_mfma_f32_16x16x32_bf16 v[104:107], v[64:67], v[198:201], v[104:107]
	v_mfma_f32_16x16x32_bf16 v[104:107], v[68:71], v[202:205], v[104:107]
	v_mfma_f32_16x16x32_bf16 v[92:95], v[48:51], v[206:209], v[92:95]
	v_mfma_f32_16x16x32_bf16 v[92:95], v[52:55], v[210:213], v[92:95]
	v_mfma_f32_16x16x32_bf16 v[88:91], v[64:67], v[206:209], v[88:91]
	v_mfma_f32_16x16x32_bf16 v[88:91], v[68:71], v[210:213], v[88:91]
	s_setprio 0
	s_barrier
	s_add_i32 s48, 0, 0x1c000
	s_add_i32 s41, s41, s51
	v_add_u32_e32 v163, s48, v174
	v_lshl_add_u64 v[160:161], v[160:161], 0, s[22:23]
	s_mov_b32 m0, s41
	ds_read_b128 v[214:217], v163
	ds_read_b128 v[218:221], v163 offset:1024
	ds_read_b128 v[222:225], v163 offset:2048
	ds_read_b128 v[226:229], v163 offset:3072
	global_load_lds_dwordx4 v[160:161], off
	v_lshl_add_u64 v[160:161], v[230:231], 0, s[22:23]
	s_add_i32 m0, s41, 0x2000
	s_nop 0
	global_load_lds_dwordx4 v[160:161], off
	s_barrier
	s_waitcnt lgkmcnt(0)
	s_setprio 1
	s_waitcnt lgkmcnt(0)
	v_mfma_f32_16x16x32_bf16 v[132:135], v[214:217], v[164:167], v[132:135]
	v_mfma_f32_16x16x32_bf16 v[132:135], v[218:221], v[168:171], v[132:135]
	v_mfma_f32_16x16x32_bf16 v[128:131], v[222:225], v[164:167], v[128:131]
	v_mfma_f32_16x16x32_bf16 v[128:131], v[226:229], v[168:171], v[128:131]
	v_mfma_f32_16x16x32_bf16 v[116:119], v[214:217], v[190:193], v[116:119]
	v_mfma_f32_16x16x32_bf16 v[116:119], v[218:221], v[194:197], v[116:119]
	v_mfma_f32_16x16x32_bf16 v[112:115], v[222:225], v[190:193], v[112:115]
	v_mfma_f32_16x16x32_bf16 v[112:115], v[226:229], v[194:197], v[112:115]
	v_mfma_f32_16x16x32_bf16 v[100:103], v[214:217], v[198:201], v[100:103]
	v_mfma_f32_16x16x32_bf16 v[100:103], v[218:221], v[202:205], v[100:103]
	v_mfma_f32_16x16x32_bf16 v[96:99], v[222:225], v[198:201], v[96:99]
	v_mfma_f32_16x16x32_bf16 v[96:99], v[226:229], v[202:205], v[96:99]
	v_mfma_f32_16x16x32_bf16 v[84:87], v[214:217], v[206:209], v[84:87]
	v_mfma_f32_16x16x32_bf16 v[84:87], v[218:221], v[210:213], v[84:87]
	v_mfma_f32_16x16x32_bf16 v[80:83], v[222:225], v[206:209], v[80:83]
	v_mfma_f32_16x16x32_bf16 v[80:83], v[226:229], v[210:213], v[80:83]
	s_setprio 0
	s_mov_b32 m0, s76
	v_lshl_add_u64 v[160:161], v[232:233], 0, s[22:23]
	s_barrier
	ds_read_b128 v[164:167], v177 offset:49152
	ds_read_b128 v[168:171], v177 offset:50176
	ds_read_b128 v[190:193], v177 offset:51200
	ds_read_b128 v[194:197], v177 offset:52224
	ds_read_b128 v[198:201], v177 offset:53248
	ds_read_b128 v[202:205], v177 offset:54272
	ds_read_b128 v[206:209], v177 offset:55296
	ds_read_b128 v[210:213], v177 offset:56320
	global_load_lds_dwordx4 v[160:161], off
	v_lshl_add_u64 v[160:161], v[234:235], 0, s[22:23]
	s_mov_b32 m0, s77
	s_nop 0
	global_load_lds_dwordx4 v[160:161], off
	s_barrier
	s_waitcnt lgkmcnt(0)
	s_setprio 1
	s_waitcnt lgkmcnt(0)
	v_mfma_f32_16x16x32_bf16 v[76:79], v[48:51], v[164:167], v[76:79]
	v_mfma_f32_16x16x32_bf16 v[76:79], v[52:55], v[168:171], v[76:79]
	v_mfma_f32_16x16x32_bf16 v[72:75], v[64:67], v[164:167], v[72:75]
	v_mfma_f32_16x16x32_bf16 v[72:75], v[68:71], v[168:171], v[72:75]
	v_mfma_f32_16x16x32_bf16 v[60:63], v[48:51], v[190:193], v[60:63]
	v_mfma_f32_16x16x32_bf16 v[60:63], v[52:55], v[194:197], v[60:63]
	v_mfma_f32_16x16x32_bf16 v[56:59], v[64:67], v[190:193], v[56:59]
	v_mfma_f32_16x16x32_bf16 v[56:59], v[68:71], v[194:197], v[56:59]
	v_mfma_f32_16x16x32_bf16 v[44:47], v[48:51], v[198:201], v[44:47]
	v_mfma_f32_16x16x32_bf16 v[44:47], v[52:55], v[202:205], v[44:47]
	v_mfma_f32_16x16x32_bf16 v[40:43], v[64:67], v[198:201], v[40:43]
	v_mfma_f32_16x16x32_bf16 v[40:43], v[68:71], v[202:205], v[40:43]
	v_mfma_f32_16x16x32_bf16 v[12:15], v[48:51], v[206:209], v[12:15]
	v_mfma_f32_16x16x32_bf16 v[12:15], v[52:55], v[210:213], v[12:15]
	v_mfma_f32_16x16x32_bf16 v[8:11], v[64:67], v[206:209], v[8:11]
	v_mfma_f32_16x16x32_bf16 v[8:11], v[68:71], v[210:213], v[8:11]
	s_setprio 0
	s_barrier
	s_add_u32 s46, s46, 0x100080
	s_addc_u32 s47, s47, 0
	s_add_i32 s41, s48, s51
	v_lshl_add_u64 v[48:49], s[46:47], 0, v[146:147]
	s_mov_b32 m0, s41
	s_nop 0
	global_load_lds_dwordx4 v[48:49], off
	v_lshl_add_u64 v[48:49], s[46:47], 0, v[150:151]
	s_add_i32 m0, s41, 0x2000
	s_nop 0
	global_load_lds_dwordx4 v[48:49], off
	s_waitcnt vmcnt(6)
	s_barrier
	s_setprio 1
	v_mfma_f32_16x16x32_bf16 v[16:19], v[214:217], v[164:167], v[16:19]
	v_mfma_f32_16x16x32_bf16 v[68:71], v[218:221], v[168:171], v[16:19]
	v_mfma_f32_16x16x32_bf16 v[16:19], v[222:225], v[164:167], v[20:23]
	v_mfma_f32_16x16x32_bf16 v[64:67], v[226:229], v[168:171], v[16:19]
	v_mfma_f32_16x16x32_bf16 v[16:19], v[214:217], v[190:193], v[32:35]
	v_mfma_f32_16x16x32_bf16 v[52:55], v[218:221], v[194:197], v[16:19]
	v_mfma_f32_16x16x32_bf16 v[16:19], v[222:225], v[190:193], v[36:39]
	v_mfma_f32_16x16x32_bf16 v[48:51], v[226:229], v[194:197], v[16:19]
	v_mfma_f32_16x16x32_bf16 v[16:19], v[214:217], v[198:201], v[28:31]
	v_mfma_f32_16x16x32_bf16 v[28:31], v[218:221], v[202:205], v[16:19]
	v_mfma_f32_16x16x32_bf16 v[16:19], v[222:225], v[198:201], v[24:27]
	v_mfma_f32_16x16x32_bf16 v[24:27], v[226:229], v[202:205], v[16:19]
	v_mfma_f32_16x16x32_bf16 v[4:7], v[214:217], v[206:209], v[4:7]
	v_mfma_f32_16x16x32_bf16 v[4:7], v[218:221], v[210:213], v[4:7]
	v_mfma_f32_16x16x32_bf16 v[0:3], v[222:225], v[206:209], v[0:3]
	v_mfma_f32_16x16x32_bf16 v[0:3], v[226:229], v[210:213], v[0:3]
	s_setprio 0
	s_add_i32 s39, s39, 2
	s_add_u32 s10, s10, 0x100
	s_addc_u32 s11, s11, 0
	s_add_u32 s13, s13, 0x100
	s_addc_u32 s15, s15, 0
	s_cmp_gt_u32 s39, 61
	s_barrier
	s_cbranch_scc0 .LBB0_604
	s_ashr_i32 s4, s12, 4
	s_cmp_eq_u32 s4, 1
	v_lshl_or_b32 v160, s12, 8, v175
	v_mov_b32_e32 v36, 0
	s_cselect_b64 s[46:47], -1, 0
	s_cmp_lg_u32 s4, 1
	v_mov_b32_e32 v37, 0
	v_mov_b32_e32 v38, 0
	v_mov_b32_e32 v39, 0
	v_mov_b32_e32 v32, 0
	v_mov_b32_e32 v33, 0
	v_mov_b32_e32 v34, 0
	v_mov_b32_e32 v35, 0
	v_mov_b32_e32 v20, 0
	v_mov_b32_e32 v21, 0
	v_mov_b32_e32 v22, 0
	v_mov_b32_e32 v23, 0
	v_mov_b32_e32 v16, 0
	v_mov_b32_e32 v17, 0
	v_mov_b32_e32 v18, 0
	v_mov_b32_e32 v19, 0
	s_cbranch_scc1 .LBB0_607
	v_mov_b32_e32 v161, v147
	v_lshl_add_u64 v[16:17], v[160:161], 2, s[18:19]
	v_add_co_u32_e32 v20, vcc, 0xffffc000, v16
	v_lshl_add_u64 v[18:19], v[16:17], 0, s[24:25]
	s_nop 0
	v_addc_co_u32_e32 v21, vcc, -1, v17, vcc
	global_load_dwordx4 v[36:39], v[20:21], off
	global_load_dwordx4 v[32:35], v[18:19], off offset:16
	v_lshl_add_u64 v[18:19], v[16:17], 0, s[26:27]
	v_add_co_u32_e32 v16, vcc, 0xffffd000, v16
	s_nop 1
	v_addc_co_u32_e32 v17, vcc, -1, v17, vcc
	global_load_dwordx4 v[20:23], v[16:17], off offset:-3584
	s_nop 0
	global_load_dwordx4 v[16:19], v[18:19], off offset:16
